# post phase reductions fully in registers: xor-32/16 steps via v_permlane32_swap / v_permlane16_swap, no ds_bpermute left in the phase
# baseline (speedup 1.0000x reference)
.LBB0_503:
	v_mad_i64_i32 v[4:5], s[0:1], v82, s15, v[8:9]
	v_lshlrev_b64 v[4:5], 1, v[4:5]
	v_lshl_add_u64 v[14:15], s[10:11], 0, v[4:5]
	v_lshl_add_u64 v[4:5], s[12:13], 0, v[4:5]
	global_load_dwordx2 v[16:17], v[14:15], off nt
	global_load_dwordx2 v[22:23], v[4:5], off nt
	v_mov_b64_e32 v[6:7], s[76:77]
	v_mad_i64_i32 v[6:7], s[0:1], v82, s69, v[6:7]
	v_lshlrev_b32_e32 v144, 1, v8
	v_lshl_add_u64 v[6:7], v[6:7], 0, v[144:145]
	s_mov_b64 s[0:1], 0xb9a3000
	v_lshl_add_u64 v[12:13], v[6:7], 0, s[0:1]
	v_add_co_u32_e32 v6, vcc, 0xb9a3000, v6
	s_nop 1
	v_addc_co_u32_e32 v7, vcc, 0, v7, vcc
	global_load_dwordx2 v[34:35], v[6:7], off nt
	global_load_dwordx2 v[24:25], v[14:15], off offset:512 nt
	global_load_dwordx2 v[26:27], v[4:5], off offset:512 nt
	global_load_dwordx2 v[76:77], v[12:13], off offset:512 nt
	global_load_dwordx2 v[28:29], v[14:15], off offset:1024 nt
	global_load_dwordx2 v[30:31], v[4:5], off offset:1024 nt
	global_load_dwordx2 v[62:63], v[12:13], off offset:1024 nt
	global_load_dwordx2 v[32:33], v[14:15], off offset:1536 nt
	global_load_dwordx2 v[38:39], v[4:5], off offset:1536 nt
	global_load_dwordx2 v[56:57], v[12:13], off offset:1536 nt
	global_load_dwordx2 v[40:41], v[14:15], off offset:2048 nt
	global_load_dwordx2 v[46:47], v[4:5], off offset:2048 nt
	global_load_dwordx2 v[42:43], v[12:13], off offset:2048 nt
	global_load_dwordx2 v[48:49], v[14:15], off offset:2560 nt
	global_load_dwordx2 v[50:51], v[4:5], off offset:2560 nt
	global_load_dwordx2 v[36:37], v[12:13], off offset:2560 nt
	global_load_dwordx2 v[52:53], v[14:15], off offset:3072 nt
	global_load_dwordx2 v[54:55], v[4:5], off offset:3072 nt
	global_load_dwordx2 v[20:21], v[12:13], off offset:3072 nt
	s_nop 0
	global_load_dwordx2 v[14:15], v[14:15], off offset:3584 nt
	s_nop 0
	global_load_dwordx2 v[68:69], v[4:5], off offset:3584 nt
	global_load_dwordx2 v[18:19], v[12:13], off offset:3584 nt
	s_waitcnt vmcnt(21)
	v_lshlrev_b32_e32 v98, 16, v34
	v_mul_f32_e32 v100, 0xbfb8aa3b, v98
	v_exp_f32_e32 v100, v100
	v_and_b32_e32 v34, 0xffff0000, v34
	v_lshlrev_b32_e32 v99, 16, v35
	v_and_b32_e32 v35, 0xffff0000, v35
	v_add_f32_e32 v100, 1.0, v100
	v_lshlrev_b32_e32 v4, 16, v16
	v_and_b32_e32 v5, 0xffff0000, v16
	v_lshlrev_b32_e32 v6, 16, v22
	v_and_b32_e32 v7, 0xffff0000, v22
	v_pk_add_f32 v[4:5], v[4:5], v[6:7]
	v_lshlrev_b32_e32 v6, 16, v17
	v_and_b32_e32 v7, 0xffff0000, v17
	v_lshlrev_b32_e32 v12, 16, v23
	v_and_b32_e32 v13, 0xffff0000, v23
	v_pk_add_f32 v[6:7], v[6:7], v[12:13]
	v_add_f32_e32 v12, v4, v5
	v_add_f32_e32 v12, v6, v12
	v_add_f32_e32 v70, v7, v12
	s_waitcnt vmcnt(20)
	v_lshlrev_b32_e32 v12, 16, v24
	v_and_b32_e32 v13, 0xffff0000, v24
	s_waitcnt vmcnt(19)
	v_lshlrev_b32_e32 v16, 16, v26
	v_and_b32_e32 v17, 0xffff0000, v26
	v_pk_add_f32 v[80:81], v[12:13], v[16:17]
	v_lshlrev_b32_e32 v12, 16, v25
	v_and_b32_e32 v13, 0xffff0000, v25
	v_lshlrev_b32_e32 v16, 16, v27
	v_and_b32_e32 v17, 0xffff0000, v27
	v_pk_add_f32 v[78:79], v[12:13], v[16:17]
	v_add_f32_e32 v12, v80, v81
	v_add_f32_e32 v12, v78, v12
	v_add_f32_e32 v26, v79, v12
	s_waitcnt vmcnt(17)
	v_lshlrev_b32_e32 v12, 16, v28
	v_and_b32_e32 v13, 0xffff0000, v28
	s_waitcnt vmcnt(16)
	v_lshlrev_b32_e32 v16, 16, v30
	v_and_b32_e32 v17, 0xffff0000, v30
	v_pk_add_f32 v[64:65], v[12:13], v[16:17]
	v_lshlrev_b32_e32 v12, 16, v29
	v_and_b32_e32 v13, 0xffff0000, v29
	v_lshlrev_b32_e32 v16, 16, v31
	v_and_b32_e32 v17, 0xffff0000, v31
	v_pk_add_f32 v[66:67], v[12:13], v[16:17]
	v_add_f32_e32 v12, v64, v65
	v_add_f32_e32 v12, v66, v12
	v_add_f32_e32 v27, v67, v12
	s_waitcnt vmcnt(14)
	v_lshlrev_b32_e32 v12, 16, v32
	v_and_b32_e32 v13, 0xffff0000, v32
	s_waitcnt vmcnt(13)
	v_lshlrev_b32_e32 v16, 16, v38
	v_and_b32_e32 v17, 0xffff0000, v38
	v_pk_add_f32 v[60:61], v[12:13], v[16:17]
	v_lshlrev_b32_e32 v12, 16, v33
	s_waitcnt lgkmcnt(0)
	v_mov_b32_e32 v32, v26
	s_nop 1
	v_permlane32_swap_b32_e32 v32, v26
	s_nop 1
	v_add_f32_e32 v26, v26, v32
	v_and_b32_e32 v13, 0xffff0000, v33
	v_lshlrev_b32_e32 v16, 16, v39
	v_and_b32_e32 v17, 0xffff0000, v39
	v_pk_add_f32 v[58:59], v[12:13], v[16:17]
	v_add_f32_e32 v12, v60, v61
	v_add_f32_e32 v12, v58, v12
	v_add_f32_e32 v28, v59, v12
	s_waitcnt vmcnt(11)
	v_lshlrev_b32_e32 v12, 16, v40
	v_and_b32_e32 v13, 0xffff0000, v40
	s_waitcnt vmcnt(10)
	v_lshlrev_b32_e32 v16, 16, v46
	v_and_b32_e32 v17, 0xffff0000, v46
	s_waitcnt lgkmcnt(0)
	v_mov_b32_e32 v32, v27
	s_nop 1
	v_permlane32_swap_b32_e32 v32, v27
	s_nop 1
	v_add_f32_e32 v27, v27, v32
	v_pk_add_f32 v[44:45], v[12:13], v[16:17]
	v_lshlrev_b32_e32 v12, 16, v41
	v_and_b32_e32 v13, 0xffff0000, v41
	v_lshlrev_b32_e32 v16, 16, v47
	v_and_b32_e32 v17, 0xffff0000, v47
	v_pk_add_f32 v[46:47], v[12:13], v[16:17]
	v_add_f32_e32 v12, v44, v45
	v_add_f32_e32 v12, v46, v12
	v_add_f32_e32 v29, v47, v12
	s_waitcnt vmcnt(8)
	v_lshlrev_b32_e32 v12, 16, v48
	v_and_b32_e32 v13, 0xffff0000, v48
	s_waitcnt vmcnt(7)
	v_lshlrev_b32_e32 v16, 16, v50
	v_and_b32_e32 v17, 0xffff0000, v50
	s_waitcnt lgkmcnt(0)
	v_mov_b32_e32 v32, v28
	s_nop 1
	v_permlane32_swap_b32_e32 v32, v28
	s_nop 1
	v_add_f32_e32 v28, v28, v32
	v_pk_add_f32 v[40:41], v[12:13], v[16:17]
	v_lshlrev_b32_e32 v12, 16, v49
	v_and_b32_e32 v13, 0xffff0000, v49
	v_lshlrev_b32_e32 v16, 16, v51
	v_and_b32_e32 v17, 0xffff0000, v51
	v_pk_add_f32 v[38:39], v[12:13], v[16:17]
	v_add_f32_e32 v12, v40, v41
	v_add_f32_e32 v12, v38, v12
	v_add_f32_e32 v30, v39, v12
	s_waitcnt vmcnt(5)
	v_lshlrev_b32_e32 v12, 16, v52
	v_and_b32_e32 v13, 0xffff0000, v52
	s_waitcnt vmcnt(4)
	v_lshlrev_b32_e32 v16, 16, v54
	v_and_b32_e32 v17, 0xffff0000, v54
	s_waitcnt lgkmcnt(0)
	v_mov_b32_e32 v32, v29
	s_nop 1
	v_permlane32_swap_b32_e32 v32, v29
	s_nop 1
	v_add_f32_e32 v29, v29, v32
	v_pk_add_f32 v[22:23], v[12:13], v[16:17]
	v_lshlrev_b32_e32 v12, 16, v53
	v_and_b32_e32 v13, 0xffff0000, v53
	v_lshlrev_b32_e32 v16, 16, v55
	v_and_b32_e32 v17, 0xffff0000, v55
	v_pk_add_f32 v[24:25], v[12:13], v[16:17]
	v_add_f32_e32 v12, v22, v23
	v_add_f32_e32 v12, v24, v12
	v_add_f32_e32 v31, v25, v12
	s_waitcnt vmcnt(2)
	v_lshlrev_b32_e32 v12, 16, v14
	v_and_b32_e32 v13, 0xffff0000, v14
	s_waitcnt vmcnt(1)
	v_lshlrev_b32_e32 v16, 16, v68
	v_and_b32_e32 v17, 0xffff0000, v68
	s_waitcnt lgkmcnt(0)
	v_mov_b32_e32 v32, v30
	s_nop 1
	v_permlane32_swap_b32_e32 v32, v30
	s_nop 1
	v_add_f32_e32 v30, v30, v32
	v_pk_add_f32 v[16:17], v[12:13], v[16:17]
	v_lshlrev_b32_e32 v12, 16, v15
	v_and_b32_e32 v13, 0xffff0000, v15
	v_lshlrev_b32_e32 v14, 16, v69
	v_and_b32_e32 v15, 0xffff0000, v69
	v_pk_add_f32 v[14:15], v[12:13], v[14:15]
	v_add_f32_e32 v12, v16, v17
	v_add_f32_e32 v12, v14, v12
	v_add_f32_e32 v12, v15, v12
	s_waitcnt lgkmcnt(0)
	v_mov_b32_e32 v32, v31
	s_nop 1
	v_permlane32_swap_b32_e32 v32, v31
	s_nop 1
	v_add_f32_e32 v31, v31, v32
	s_waitcnt lgkmcnt(0)
	v_mov_b32_e32 v13, v70
	s_nop 1
	v_permlane32_swap_b32_e32 v13, v70
	s_nop 1
	v_add_f32_e32 v13, v70, v13
	s_waitcnt lgkmcnt(0)
	v_mov_b32_e32 v32, v12
	s_nop 1
	v_permlane32_swap_b32_e32 v32, v12
	s_nop 1
	v_add_f32_e32 v12, v12, v32
	s_waitcnt lgkmcnt(0)
	v_mov_b32_e32 v32, v13
	s_nop 1
	v_permlane16_swap_b32_e32 v32, v13
	s_nop 1
	v_add_f32_e32 v13, v13, v32
	s_waitcnt lgkmcnt(0)
	v_mov_b32_e32 v32, v26
	s_nop 1
	v_permlane16_swap_b32_e32 v32, v26
	s_nop 1
	v_add_f32_e32 v26, v26, v32
	v_rcp_f32_e32 v101, v100
	s_nop 0
	v_mul_f32_e32 v98, v98, v101
	v_mul_f32_e32 v100, 0xbfb8aa3b, v34
	v_exp_f32_e32 v100, v100
	s_waitcnt lgkmcnt(0)
	v_mov_b32_e32 v32, v27
	s_nop 1
	v_permlane16_swap_b32_e32 v32, v27
	s_nop 1
	v_add_f32_e32 v27, v27, v32
	v_add_f32_e32 v100, 1.0, v100
	s_waitcnt lgkmcnt(0)
	v_mov_b32_e32 v32, v28
	s_nop 1
	v_permlane16_swap_b32_e32 v32, v28
	s_nop 1
	v_add_f32_e32 v28, v28, v32
	s_waitcnt lgkmcnt(0)
	v_mov_b32_e32 v32, v29
	s_nop 1
	v_permlane16_swap_b32_e32 v32, v29
	s_nop 1
	v_add_f32_e32 v29, v29, v32
	s_waitcnt lgkmcnt(0)
	v_mov_b32_e32 v32, v30
	s_nop 1
	v_permlane16_swap_b32_e32 v32, v30
	s_nop 1
	v_add_f32_e32 v30, v30, v32
	s_waitcnt lgkmcnt(0)
	v_mov_b32_e32 v32, v31
	s_nop 1
	v_permlane16_swap_b32_e32 v32, v31
	s_nop 1
	v_add_f32_e32 v31, v31, v32
	v_rcp_f32_e32 v101, v100
	s_nop 0
	v_mul_f32_e32 v100, v34, v101
	v_mul_f32_e32 v34, 0xbfb8aa3b, v99
	v_exp_f32_e32 v34, v34
	s_waitcnt lgkmcnt(0)
	v_mov_b32_e32 v32, v12
	s_nop 1
	v_permlane16_swap_b32_e32 v32, v12
	s_nop 1
	v_add_f32_e32 v12, v12, v32
	v_add_f32_e32 v34, 1.0, v34
	s_waitcnt lgkmcnt(0)
	s_nop 1
	v_add_f32_dpp v13, v13, v13 row_mirror row_mask:0xf bank_mask:0xf
	s_waitcnt lgkmcnt(0)
	s_nop 1
	v_add_f32_dpp v26, v26, v26 row_mirror row_mask:0xf bank_mask:0xf
	s_waitcnt lgkmcnt(0)
	s_nop 1
	v_add_f32_dpp v27, v27, v27 row_mirror row_mask:0xf bank_mask:0xf
	s_waitcnt lgkmcnt(0)
	s_nop 1
	v_add_f32_dpp v28, v28, v28 row_mirror row_mask:0xf bank_mask:0xf
	v_rcp_f32_e32 v101, v34
	s_nop 0
	v_mul_f32_e32 v99, v99, v101
	v_mul_f32_e32 v34, 0xbfb8aa3b, v35
	v_exp_f32_e32 v34, v34
	s_waitcnt lgkmcnt(0)
	s_nop 1
	v_add_f32_dpp v29, v29, v29 row_mirror row_mask:0xf bank_mask:0xf
	v_add_f32_e32 v34, 1.0, v34
	s_waitcnt lgkmcnt(0)
	s_nop 1
	v_add_f32_dpp v30, v30, v30 row_mirror row_mask:0xf bank_mask:0xf
	s_waitcnt lgkmcnt(0)
	s_nop 1
	v_add_f32_dpp v31, v31, v31 row_mirror row_mask:0xf bank_mask:0xf
	s_waitcnt lgkmcnt(0)
	s_nop 1
	v_add_f32_dpp v12, v12, v12 row_mirror row_mask:0xf bank_mask:0xf
	s_waitcnt lgkmcnt(0)
	s_nop 1
	v_add_f32_dpp v13, v13, v13 row_half_mirror row_mask:0xf bank_mask:0xf
	v_rcp_f32_e32 v101, v34
	s_nop 0
	v_mul_f32_e32 v101, v35, v101
	s_waitcnt lgkmcnt(0)
	s_nop 1
	v_add_f32_dpp v26, v26, v26 row_half_mirror row_mask:0xf bank_mask:0xf
	s_waitcnt lgkmcnt(0)
	s_nop 1
	v_add_f32_dpp v27, v27, v27 row_half_mirror row_mask:0xf bank_mask:0xf
	s_waitcnt lgkmcnt(0)
	s_nop 1
	v_add_f32_dpp v28, v28, v28 row_half_mirror row_mask:0xf bank_mask:0xf
	s_waitcnt lgkmcnt(0)
	s_nop 1
	v_add_f32_dpp v29, v29, v29 row_half_mirror row_mask:0xf bank_mask:0xf
	s_waitcnt lgkmcnt(0)
	s_nop 1
	v_add_f32_dpp v30, v30, v30 row_half_mirror row_mask:0xf bank_mask:0xf
	s_waitcnt lgkmcnt(0)
	s_nop 1
	v_add_f32_dpp v31, v31, v31 row_half_mirror row_mask:0xf bank_mask:0xf
	s_waitcnt lgkmcnt(0)
	s_nop 1
	v_add_f32_dpp v12, v12, v12 row_half_mirror row_mask:0xf bank_mask:0xf
	s_waitcnt lgkmcnt(0)
	s_nop 1
	v_add_f32_dpp v13, v13, v13 quad_perm:[2,3,0,1] row_mask:0xf bank_mask:0xf
	s_waitcnt lgkmcnt(0)
	s_nop 1
	v_add_f32_dpp v26, v26, v26 quad_perm:[2,3,0,1] row_mask:0xf bank_mask:0xf
	s_waitcnt lgkmcnt(0)
	s_nop 1
	v_add_f32_dpp v27, v27, v27 quad_perm:[2,3,0,1] row_mask:0xf bank_mask:0xf
	s_waitcnt lgkmcnt(0)
	s_nop 1
	v_add_f32_dpp v28, v28, v28 quad_perm:[2,3,0,1] row_mask:0xf bank_mask:0xf
	s_waitcnt lgkmcnt(0)
	s_nop 1
	v_add_f32_dpp v29, v29, v29 quad_perm:[2,3,0,1] row_mask:0xf bank_mask:0xf
	s_waitcnt lgkmcnt(0)
	s_nop 1
	v_add_f32_dpp v30, v30, v30 quad_perm:[2,3,0,1] row_mask:0xf bank_mask:0xf
	s_waitcnt lgkmcnt(0)
	s_nop 1
	v_add_f32_dpp v31, v31, v31 quad_perm:[2,3,0,1] row_mask:0xf bank_mask:0xf
	s_waitcnt lgkmcnt(0)
	s_nop 1
	v_add_f32_dpp v12, v12, v12 quad_perm:[2,3,0,1] row_mask:0xf bank_mask:0xf
	s_waitcnt lgkmcnt(0)
	s_nop 1
	v_add_f32_dpp v13, v13, v13 quad_perm:[1,0,3,2] row_mask:0xf bank_mask:0xf
	v_fmamk_f32 v5, v13, 0xbb800000, v5
	v_fmac_f32_e32 v4, 0xbb800000, v13
	v_fmamk_f32 v7, v13, 0xbb800000, v7
	v_fmac_f32_e32 v6, 0xbb800000, v13
	s_waitcnt lgkmcnt(0)
	s_nop 1
	v_add_f32_dpp v26, v26, v26 quad_perm:[1,0,3,2] row_mask:0xf bank_mask:0xf
	v_fmamk_f32 v81, v26, 0xbb800000, v81
	v_fmac_f32_e32 v80, 0xbb800000, v26
	v_pk_mul_f32 v[92:93], v[4:5], v[4:5]
	v_fmamk_f32 v79, v26, 0xbb800000, v79
	v_fmac_f32_e32 v78, 0xbb800000, v26
	v_pk_mul_f32 v[96:97], v[80:81], v[80:81]
	v_pk_mul_f32 v[90:91], v[6:7], v[6:7]
	v_pk_mul_f32 v[94:95], v[78:79], v[78:79]
	v_mov_b32_e32 v34, v96
	v_mov_b32_e32 v35, v92
	v_mov_b32_e32 v92, v97
	v_pk_add_f32 v[34:35], v[34:35], v[92:93]
	v_mov_b32_e32 v92, v94
	v_mov_b32_e32 v93, v90
	v_pk_add_f32 v[34:35], v[92:93], v[34:35]
	v_mov_b32_e32 v90, v95
	v_pk_add_f32 v[34:35], v[90:91], v[34:35]
	s_waitcnt lgkmcnt(0)
	v_mov_b32_e32 v90, v34
	v_mov_b32_e32 v91, v35
	s_nop 1
	v_permlane32_swap_b32_e32 v90, v34
	v_permlane32_swap_b32_e32 v91, v35
	s_nop 1
	v_pk_add_f32 v[34:35], v[34:35], v[90:91]
	s_waitcnt lgkmcnt(0)
	s_nop 1
	v_add_f32_dpp v27, v27, v27 quad_perm:[1,0,3,2] row_mask:0xf bank_mask:0xf
	v_fmamk_f32 v65, v27, 0xbb800000, v65
	v_fmac_f32_e32 v64, 0xbb800000, v27
	s_waitcnt lgkmcnt(0)
	v_mov_b32_e32 v90, v34
	v_mov_b32_e32 v91, v35
	s_nop 1
	v_permlane16_swap_b32_e32 v90, v34
	v_permlane16_swap_b32_e32 v91, v35
	s_nop 1
	v_pk_add_f32 v[34:35], v[34:35], v[90:91]
	s_waitcnt lgkmcnt(0)
	s_nop 1
	v_add_f32_dpp v28, v28, v28 quad_perm:[1,0,3,2] row_mask:0xf bank_mask:0xf
	v_fmamk_f32 v61, v28, 0xbb800000, v61
	v_fmac_f32_e32 v60, 0xbb800000, v28
	v_fmamk_f32 v67, v27, 0xbb800000, v67
	s_waitcnt lgkmcnt(0)
	s_nop 1
	v_add_f32_dpp v29, v29, v29 quad_perm:[1,0,3,2] row_mask:0xf bank_mask:0xf
	s_waitcnt lgkmcnt(0)
	s_nop 1
	v_add_f32_dpp v35, v35, v35 row_mirror row_mask:0xf bank_mask:0xf
	v_add_f32_dpp v34, v34, v34 row_mirror row_mask:0xf bank_mask:0xf
	v_fmac_f32_e32 v66, 0xbb800000, v27
	s_waitcnt lgkmcnt(0)
	s_nop 1
	v_add_f32_dpp v30, v30, v30 quad_perm:[1,0,3,2] row_mask:0xf bank_mask:0xf
	v_pk_mul_f32 v[70:71], v[64:65], v[64:65]
	s_waitcnt lgkmcnt(0)
	s_nop 1
	v_add_f32_dpp v35, v35, v35 row_half_mirror row_mask:0xf bank_mask:0xf
	v_add_f32_dpp v34, v34, v34 row_half_mirror row_mask:0xf bank_mask:0xf
	s_waitcnt lgkmcnt(0)
	s_nop 1
	v_add_f32_dpp v31, v31, v31 quad_perm:[1,0,3,2] row_mask:0xf bank_mask:0xf
	v_fmamk_f32 v59, v28, 0xbb800000, v59
	v_fmac_f32_e32 v58, 0xbb800000, v28
	s_waitcnt lgkmcnt(0)
	s_nop 1
	v_add_f32_dpp v35, v35, v35 quad_perm:[2,3,0,1] row_mask:0xf bank_mask:0xf
	v_add_f32_dpp v34, v34, v34 quad_perm:[2,3,0,1] row_mask:0xf bank_mask:0xf
	s_waitcnt lgkmcnt(0)
	s_nop 1
	v_add_f32_dpp v12, v12, v12 quad_perm:[1,0,3,2] row_mask:0xf bank_mask:0xf
	v_fmamk_f32 v17, v12, 0xbb800000, v17
	v_fmac_f32_e32 v16, 0xbb800000, v12
	v_fmamk_f32 v15, v12, 0xbb800000, v15
	v_fmac_f32_e32 v14, 0xbb800000, v12
	v_mad_i64_i32 v[12:13], s[0:1], v82, s70, v[10:11]
	s_mov_b32 s0, 0x358637bd
	s_waitcnt lgkmcnt(0)
	s_nop 1
	v_add_f32_dpp v91, v35, v35 quad_perm:[1,0,3,2] row_mask:0xf bank_mask:0xf
	v_add_f32_dpp v90, v34, v34 quad_perm:[1,0,3,2] row_mask:0xf bank_mask:0xf
	v_mov_b64_e32 v[34:35], s[0:1]
	v_pk_fma_f32 v[90:91], v[90:91], s[34:35], v[34:35] op_sel_hi:[1,0,0]
	v_pk_mul_f32 v[74:75], v[60:61], v[60:61]
	v_mul_f32_e32 v92, 0x4b800000, v91
	v_cmp_gt_f32_e64 s[0:1], s72, v91
	v_cmp_gt_f32_e32 vcc, s72, v90
	v_pk_mul_f32 v[68:69], v[66:67], v[66:67]
	v_cndmask_b32_e64 v91, v91, v92, s[0:1]
	v_rsq_f32_e32 v91, v91
	v_pk_mul_f32 v[72:73], v[58:59], v[58:59]
	v_fmamk_f32 v45, v29, 0xbb800000, v45
	v_fmac_f32_e32 v44, 0xbb800000, v29
	v_mul_f32_e32 v92, 0x45800000, v91
	v_cndmask_b32_e64 v91, v91, v92, s[0:1]
	v_mul_f32_e32 v4, v4, v91
	v_mul_f32_e32 v5, v5, v91
	v_mul_f32_e32 v4, v0, v4
	v_mul_f32_e32 v5, v1, v5
	v_mul_f32_e32 v4, v98, v4
	v_mul_f32_e32 v5, v100, v5
	v_cvt_pk_bf16_f32 v4, v4, v5
	v_mul_f32_e32 v5, v6, v91
	v_mul_f32_e32 v5, v2, v5
	v_mul_f32_e32 v6, v7, v91
	v_mul_f32_e32 v5, v99, v5
	v_mul_f32_e32 v6, v3, v6
	v_mul_f32_e32 v6, v101, v6
	v_cvt_pk_bf16_f32 v5, v5, v6
	global_store_dwordx2 v[12:13], v[4:5], off
	v_mul_f32_e32 v4, 0x4b800000, v90
	v_cndmask_b32_e32 v4, v90, v4, vcc
	v_rsq_f32_e32 v4, v4
	v_lshlrev_b32_e32 v91, 16, v76
	v_and_b32_e32 v76, 0xffff0000, v76
	v_lshlrev_b32_e32 v92, 16, v77
	v_mul_f32_e32 v5, 0x45800000, v4
	v_cndmask_b32_e32 v90, v4, v5, vcc
	ds_read_b128 v[4:7], v83 offset:1024
	v_mul_f32_e32 v80, v80, v90
	v_and_b32_e32 v77, 0xffff0000, v77
	v_fmamk_f32 v41, v30, 0xbb800000, v41
	v_fmac_f32_e32 v40, 0xbb800000, v30
	s_waitcnt lgkmcnt(0)
	v_mul_f32_e32 v4, v80, v4
	v_mul_f32_e32 v80, 0xbfb8aa3b, v91
	v_exp_f32_e32 v80, v80
	v_fmamk_f32 v47, v29, 0xbb800000, v47
	v_fmac_f32_e32 v46, 0xbb800000, v29
	v_pk_mul_f32 v[50:51], v[44:45], v[44:45]
	v_add_f32_e32 v80, 1.0, v80
	v_fmamk_f32 v39, v30, 0xbb800000, v39
	v_fmac_f32_e32 v38, 0xbb800000, v30
	v_pk_mul_f32 v[54:55], v[40:41], v[40:41]
	v_rcp_f32_e32 v93, v80
	s_nop 0
	v_mul_f32_e32 v80, v91, v93
	v_mul_f32_e32 v4, v80, v4
	v_mul_f32_e32 v80, v81, v90
	v_mul_f32_e32 v5, v80, v5
	v_mul_f32_e32 v80, 0xbfb8aa3b, v76
	v_exp_f32_e32 v80, v80
	v_pk_mul_f32 v[48:49], v[46:47], v[46:47]
	v_pk_mul_f32 v[52:53], v[38:39], v[38:39]
	v_fmamk_f32 v23, v31, 0xbb800000, v23
	v_add_f32_e32 v80, 1.0, v80
	v_fmac_f32_e32 v22, 0xbb800000, v31
	v_fmamk_f32 v25, v31, 0xbb800000, v25
	v_fmac_f32_e32 v24, 0xbb800000, v31
	v_rcp_f32_e32 v81, v80
	s_nop 0
	v_mul_f32_e32 v76, v76, v81
	v_mul_f32_e32 v5, v76, v5
	v_cvt_pk_bf16_f32 v4, v4, v5
	v_mul_f32_e32 v5, v78, v90
	v_mul_f32_e32 v5, v5, v6
	v_mul_f32_e32 v6, 0xbfb8aa3b, v92
	v_exp_f32_e32 v6, v6
	v_pk_mul_f32 v[28:29], v[22:23], v[22:23]
	v_pk_mul_f32 v[32:33], v[16:17], v[16:17]
	v_pk_mul_f32 v[26:27], v[24:25], v[24:25]
	v_add_f32_e32 v6, 1.0, v6
	v_pk_mul_f32 v[30:31], v[14:15], v[14:15]
	v_add_u32_e32 v82, s14, v82
	v_rcp_f32_e32 v76, v6
	s_nop 0
	v_mul_f32_e32 v6, v92, v76
	v_mul_f32_e32 v5, v6, v5
	v_mul_f32_e32 v6, v79, v90
	v_mul_f32_e32 v6, v6, v7
	v_mul_f32_e32 v7, 0xbfb8aa3b, v77
	v_exp_f32_e32 v7, v7
	s_nop 0
	v_add_f32_e32 v7, 1.0, v7
	s_nop 0
	v_rcp_f32_e32 v76, v7
	s_nop 0
	v_mul_f32_e32 v7, v77, v76
	v_lshlrev_b32_e32 v76, 16, v62
	v_mul_f32_e32 v78, 0xbfb8aa3b, v76
	v_exp_f32_e32 v78, v78
	v_and_b32_e32 v62, 0xffff0000, v62
	v_lshlrev_b32_e32 v77, 16, v63
	v_and_b32_e32 v63, 0xffff0000, v63
	v_add_f32_e32 v78, 1.0, v78
	v_mul_f32_e32 v6, v7, v6
	v_cvt_pk_bf16_f32 v5, v5, v6
	global_store_dwordx2 v[12:13], v[4:5], off offset:512
	v_rcp_f32_e32 v79, v78
	s_nop 0
	v_mul_f32_e32 v76, v76, v79
	v_mul_f32_e32 v78, 0xbfb8aa3b, v62
	v_exp_f32_e32 v78, v78
	ds_read_b128 v[4:7], v83 offset:2048
	v_add_f32_e32 v78, 1.0, v78
	s_nop 0
	v_rcp_f32_e32 v79, v78
	s_nop 0
	v_mul_f32_e32 v78, v62, v79
	v_mul_f32_e32 v62, 0xbfb8aa3b, v77
	v_exp_f32_e32 v62, v62
	s_nop 0
	v_add_f32_e32 v62, 1.0, v62
	s_nop 0
	v_rcp_f32_e32 v79, v62
	s_nop 0
	v_mul_f32_e32 v77, v77, v79
	v_mul_f32_e32 v62, 0xbfb8aa3b, v63
	v_exp_f32_e32 v62, v62
	s_nop 0
	v_add_f32_e32 v62, 1.0, v62
	s_nop 0
	v_rcp_f32_e32 v79, v62
	s_nop 0
	v_mul_f32_e32 v79, v63, v79
	v_mov_b32_e32 v62, v74
	v_mov_b32_e32 v63, v70
	v_mov_b32_e32 v70, v75
	v_pk_add_f32 v[62:63], v[62:63], v[70:71]
	v_mov_b32_e32 v70, v72
	v_mov_b32_e32 v71, v68
	v_pk_add_f32 v[62:63], v[70:71], v[62:63]
	v_mov_b32_e32 v68, v73
	v_pk_add_f32 v[62:63], v[68:69], v[62:63]
	s_waitcnt lgkmcnt(0)
	v_mov_b32_e32 v68, v62
	v_mov_b32_e32 v69, v63
	s_nop 1
	v_permlane32_swap_b32_e32 v68, v62
	v_permlane32_swap_b32_e32 v69, v63
	s_nop 1
	v_pk_add_f32 v[62:63], v[62:63], v[68:69]
	s_waitcnt lgkmcnt(0)
	v_mov_b32_e32 v68, v62
	v_mov_b32_e32 v69, v63
	s_nop 1
	v_permlane16_swap_b32_e32 v68, v62
	v_permlane16_swap_b32_e32 v69, v63
	s_nop 1
	v_pk_add_f32 v[62:63], v[62:63], v[68:69]
	s_waitcnt lgkmcnt(0)
	s_nop 1
	v_add_f32_dpp v63, v63, v63 row_mirror row_mask:0xf bank_mask:0xf
	v_add_f32_dpp v62, v62, v62 row_mirror row_mask:0xf bank_mask:0xf
	s_waitcnt lgkmcnt(0)
	s_nop 1
	v_add_f32_dpp v63, v63, v63 row_half_mirror row_mask:0xf bank_mask:0xf
	v_add_f32_dpp v62, v62, v62 row_half_mirror row_mask:0xf bank_mask:0xf
	s_waitcnt lgkmcnt(0)
	s_nop 1
	v_add_f32_dpp v63, v63, v63 quad_perm:[2,3,0,1] row_mask:0xf bank_mask:0xf
	v_add_f32_dpp v62, v62, v62 quad_perm:[2,3,0,1] row_mask:0xf bank_mask:0xf
	s_waitcnt lgkmcnt(0)
	s_nop 1
	v_add_f32_dpp v63, v63, v63 quad_perm:[1,0,3,2] row_mask:0xf bank_mask:0xf
	v_add_f32_dpp v62, v62, v62 quad_perm:[1,0,3,2] row_mask:0xf bank_mask:0xf
	s_nop 0
	v_pk_fma_f32 v[62:63], v[62:63], s[34:35], v[34:35] op_sel_hi:[1,0,0]
	s_nop 0
	v_mul_f32_e32 v68, 0x4b800000, v63
	v_cmp_gt_f32_e64 s[0:1], s72, v63
	v_cmp_gt_f32_e32 vcc, s72, v62
	s_nop 0
	v_cndmask_b32_e64 v63, v63, v68, s[0:1]
	v_rsq_f32_e32 v63, v63
	s_nop 0
	v_mul_f32_e32 v68, 0x45800000, v63
	v_cndmask_b32_e64 v63, v63, v68, s[0:1]
	v_mul_f32_e32 v64, v64, v63
	v_mul_f32_e32 v4, v64, v4
	v_mul_f32_e32 v64, v65, v63
	v_mul_f32_e32 v5, v64, v5
	v_mul_f32_e32 v4, v76, v4
	v_mul_f32_e32 v5, v78, v5
	v_cvt_pk_bf16_f32 v4, v4, v5
	v_mul_f32_e32 v5, v66, v63
	v_mul_f32_e32 v5, v5, v6
	v_mul_f32_e32 v6, v67, v63
	v_mul_f32_e32 v5, v77, v5
	v_mul_f32_e32 v6, v6, v7
	v_mul_f32_e32 v6, v79, v6
	v_cvt_pk_bf16_f32 v5, v5, v6
	global_store_dwordx2 v[12:13], v[4:5], off offset:1024
	v_mul_f32_e32 v4, 0x4b800000, v62
	v_cndmask_b32_e32 v4, v62, v4, vcc
	v_rsq_f32_e32 v4, v4
	v_lshlrev_b32_e32 v63, 16, v56
	v_and_b32_e32 v56, 0xffff0000, v56
	v_lshlrev_b32_e32 v64, 16, v57
	v_mul_f32_e32 v5, 0x45800000, v4
	v_cndmask_b32_e32 v62, v4, v5, vcc
	ds_read_b128 v[4:7], v83 offset:3072
	v_mul_f32_e32 v60, v60, v62
	v_and_b32_e32 v57, 0xffff0000, v57
	s_waitcnt lgkmcnt(0)
	v_mul_f32_e32 v4, v60, v4
	v_mul_f32_e32 v60, 0xbfb8aa3b, v63
	v_exp_f32_e32 v60, v60
	s_nop 0
	v_add_f32_e32 v60, 1.0, v60
	s_nop 0
	v_rcp_f32_e32 v65, v60
	s_nop 0
	v_mul_f32_e32 v60, v63, v65
	v_mul_f32_e32 v4, v60, v4
	v_mul_f32_e32 v60, v61, v62
	v_mul_f32_e32 v5, v60, v5
	v_mul_f32_e32 v60, 0xbfb8aa3b, v56
	v_exp_f32_e32 v60, v60
	s_nop 0
	v_add_f32_e32 v60, 1.0, v60
	s_nop 0
	v_rcp_f32_e32 v61, v60
	s_nop 0
	v_mul_f32_e32 v56, v56, v61
	v_mul_f32_e32 v5, v56, v5
	v_cvt_pk_bf16_f32 v4, v4, v5
	v_mul_f32_e32 v5, v58, v62
	v_mul_f32_e32 v5, v5, v6
	v_mul_f32_e32 v6, 0xbfb8aa3b, v64
	v_exp_f32_e32 v6, v6
	s_nop 0
	v_add_f32_e32 v6, 1.0, v6
	s_nop 0
	v_rcp_f32_e32 v56, v6
	s_nop 0
	v_mul_f32_e32 v6, v64, v56
	v_mul_f32_e32 v5, v6, v5
	v_mul_f32_e32 v6, v59, v62
	v_mul_f32_e32 v6, v6, v7
	v_mul_f32_e32 v7, 0xbfb8aa3b, v57
	v_exp_f32_e32 v7, v7
	s_nop 0
	v_add_f32_e32 v7, 1.0, v7
	s_nop 0
	v_rcp_f32_e32 v56, v7
	s_nop 0
	v_mul_f32_e32 v7, v57, v56
	v_lshlrev_b32_e32 v56, 16, v42
	v_mul_f32_e32 v58, 0xbfb8aa3b, v56
	v_exp_f32_e32 v58, v58
	v_and_b32_e32 v42, 0xffff0000, v42
	v_lshlrev_b32_e32 v57, 16, v43
	v_and_b32_e32 v43, 0xffff0000, v43
	v_add_f32_e32 v58, 1.0, v58
	v_mul_f32_e32 v6, v7, v6
	v_cvt_pk_bf16_f32 v5, v5, v6
	global_store_dwordx2 v[12:13], v[4:5], off offset:1536
	v_rcp_f32_e32 v59, v58
	s_nop 0
	v_mul_f32_e32 v56, v56, v59
	v_mul_f32_e32 v58, 0xbfb8aa3b, v42
	v_exp_f32_e32 v58, v58
	ds_read_b128 v[4:7], v83 offset:4096
	v_add_f32_e32 v58, 1.0, v58
	s_nop 0
	v_rcp_f32_e32 v59, v58
	s_nop 0
	v_mul_f32_e32 v58, v42, v59
	v_mul_f32_e32 v42, 0xbfb8aa3b, v57
	v_exp_f32_e32 v42, v42
	s_nop 0
	v_add_f32_e32 v42, 1.0, v42
	s_nop 0
	v_rcp_f32_e32 v59, v42
	s_nop 0
	v_mul_f32_e32 v57, v57, v59
	v_mul_f32_e32 v42, 0xbfb8aa3b, v43
	v_exp_f32_e32 v42, v42
	s_nop 0
	v_add_f32_e32 v42, 1.0, v42
	s_nop 0
	v_rcp_f32_e32 v59, v42
	s_nop 0
	v_mul_f32_e32 v59, v43, v59
	v_mov_b32_e32 v42, v54
	v_mov_b32_e32 v43, v50
	v_mov_b32_e32 v50, v55
	v_pk_add_f32 v[42:43], v[42:43], v[50:51]
	v_mov_b32_e32 v50, v52
	v_mov_b32_e32 v51, v48
	v_pk_add_f32 v[42:43], v[50:51], v[42:43]
	v_mov_b32_e32 v48, v53
	v_pk_add_f32 v[42:43], v[48:49], v[42:43]
	s_waitcnt lgkmcnt(0)
	v_mov_b32_e32 v48, v42
	v_mov_b32_e32 v49, v43
	s_nop 1
	v_permlane32_swap_b32_e32 v48, v42
	v_permlane32_swap_b32_e32 v49, v43
	s_nop 1
	v_pk_add_f32 v[42:43], v[42:43], v[48:49]
	s_waitcnt lgkmcnt(0)
	v_mov_b32_e32 v48, v42
	v_mov_b32_e32 v49, v43
	s_nop 1
	v_permlane16_swap_b32_e32 v48, v42
	v_permlane16_swap_b32_e32 v49, v43
	s_nop 1
	v_pk_add_f32 v[42:43], v[42:43], v[48:49]
	s_waitcnt lgkmcnt(0)
	s_nop 1
	v_add_f32_dpp v43, v43, v43 row_mirror row_mask:0xf bank_mask:0xf
	v_add_f32_dpp v42, v42, v42 row_mirror row_mask:0xf bank_mask:0xf
	s_waitcnt lgkmcnt(0)
	s_nop 1
	v_add_f32_dpp v43, v43, v43 row_half_mirror row_mask:0xf bank_mask:0xf
	v_add_f32_dpp v42, v42, v42 row_half_mirror row_mask:0xf bank_mask:0xf
	s_waitcnt lgkmcnt(0)
	s_nop 1
	v_add_f32_dpp v43, v43, v43 quad_perm:[2,3,0,1] row_mask:0xf bank_mask:0xf
	v_add_f32_dpp v42, v42, v42 quad_perm:[2,3,0,1] row_mask:0xf bank_mask:0xf
	s_waitcnt lgkmcnt(0)
	s_nop 1
	v_add_f32_dpp v43, v43, v43 quad_perm:[1,0,3,2] row_mask:0xf bank_mask:0xf
	v_add_f32_dpp v42, v42, v42 quad_perm:[1,0,3,2] row_mask:0xf bank_mask:0xf
	s_nop 0
	v_pk_fma_f32 v[42:43], v[42:43], s[34:35], v[34:35] op_sel_hi:[1,0,0]
	s_nop 0
	v_mul_f32_e32 v48, 0x4b800000, v43
	v_cmp_gt_f32_e64 s[0:1], s72, v43
	v_cmp_gt_f32_e32 vcc, s72, v42
	s_nop 0
	v_cndmask_b32_e64 v43, v43, v48, s[0:1]
	v_rsq_f32_e32 v43, v43
	s_nop 0
	v_mul_f32_e32 v48, 0x45800000, v43
	v_cndmask_b32_e64 v43, v43, v48, s[0:1]
	v_mul_f32_e32 v44, v44, v43
	v_mul_f32_e32 v4, v44, v4
	v_mul_f32_e32 v44, v45, v43
	v_mul_f32_e32 v5, v44, v5
	v_mul_f32_e32 v4, v56, v4
	v_mul_f32_e32 v5, v58, v5
	v_cvt_pk_bf16_f32 v4, v4, v5
	v_mul_f32_e32 v5, v46, v43
	v_mul_f32_e32 v5, v5, v6
	v_mul_f32_e32 v6, v47, v43
	v_mul_f32_e32 v5, v57, v5
	v_mul_f32_e32 v6, v6, v7
	v_mul_f32_e32 v6, v59, v6
	v_cvt_pk_bf16_f32 v5, v5, v6
	global_store_dwordx2 v[12:13], v[4:5], off offset:2048
	v_mul_f32_e32 v4, 0x4b800000, v42
	v_cndmask_b32_e32 v4, v42, v4, vcc
	v_rsq_f32_e32 v4, v4
	v_lshlrev_b32_e32 v43, 16, v36
	v_and_b32_e32 v36, 0xffff0000, v36
	v_lshlrev_b32_e32 v44, 16, v37
	v_mul_f32_e32 v5, 0x45800000, v4
	v_cndmask_b32_e32 v42, v4, v5, vcc
	ds_read_b128 v[4:7], v83 offset:5120
	v_mul_f32_e32 v40, v40, v42
	v_and_b32_e32 v37, 0xffff0000, v37
	s_waitcnt lgkmcnt(0)
	v_mul_f32_e32 v4, v40, v4
	v_mul_f32_e32 v40, 0xbfb8aa3b, v43
	v_exp_f32_e32 v40, v40
	s_nop 0
	v_add_f32_e32 v40, 1.0, v40
	s_nop 0
	v_rcp_f32_e32 v45, v40
	s_nop 0
	v_mul_f32_e32 v40, v43, v45
	v_mul_f32_e32 v4, v40, v4
	v_mul_f32_e32 v40, v41, v42
	v_mul_f32_e32 v5, v40, v5
	v_mul_f32_e32 v40, 0xbfb8aa3b, v36
	v_exp_f32_e32 v40, v40
	s_nop 0
	v_add_f32_e32 v40, 1.0, v40
	s_nop 0
	v_rcp_f32_e32 v41, v40
	s_nop 0
	v_mul_f32_e32 v36, v36, v41
	v_mul_f32_e32 v5, v36, v5
	v_cvt_pk_bf16_f32 v4, v4, v5
	v_mul_f32_e32 v5, v38, v42
	v_mul_f32_e32 v5, v5, v6
	v_mul_f32_e32 v6, 0xbfb8aa3b, v44
	v_exp_f32_e32 v6, v6
	s_nop 0
	v_add_f32_e32 v6, 1.0, v6
	s_nop 0
	v_rcp_f32_e32 v36, v6
	s_nop 0
	v_mul_f32_e32 v6, v44, v36
	v_mul_f32_e32 v5, v6, v5
	v_mul_f32_e32 v6, v39, v42
	v_mul_f32_e32 v6, v6, v7
	v_mul_f32_e32 v7, 0xbfb8aa3b, v37
	v_exp_f32_e32 v7, v7
	s_nop 0
	v_add_f32_e32 v7, 1.0, v7
	s_nop 0
	v_rcp_f32_e32 v36, v7
	s_nop 0
	v_mul_f32_e32 v7, v37, v36
	v_lshlrev_b32_e32 v36, 16, v20
	v_mul_f32_e32 v38, 0xbfb8aa3b, v36
	v_exp_f32_e32 v38, v38
	v_and_b32_e32 v20, 0xffff0000, v20
	v_lshlrev_b32_e32 v37, 16, v21
	v_and_b32_e32 v21, 0xffff0000, v21
	v_add_f32_e32 v38, 1.0, v38
	v_mul_f32_e32 v6, v7, v6
	v_cvt_pk_bf16_f32 v5, v5, v6
	global_store_dwordx2 v[12:13], v[4:5], off offset:2560
	v_rcp_f32_e32 v39, v38
	s_nop 0
	v_mul_f32_e32 v36, v36, v39
	v_mul_f32_e32 v38, 0xbfb8aa3b, v20
	v_exp_f32_e32 v38, v38
	ds_read_b128 v[4:7], v83 offset:6144
	v_add_f32_e32 v38, 1.0, v38
	s_nop 0
	v_rcp_f32_e32 v39, v38
	s_nop 0
	v_mul_f32_e32 v38, v20, v39
	v_mul_f32_e32 v20, 0xbfb8aa3b, v37
	v_exp_f32_e32 v20, v20
	s_nop 0
	v_add_f32_e32 v20, 1.0, v20
	s_nop 0
	v_rcp_f32_e32 v39, v20
	s_nop 0
	v_mul_f32_e32 v37, v37, v39
	v_mul_f32_e32 v20, 0xbfb8aa3b, v21
	v_exp_f32_e32 v20, v20
	s_nop 0
	v_add_f32_e32 v20, 1.0, v20
	s_nop 0
	v_rcp_f32_e32 v39, v20
	s_nop 0
	v_mul_f32_e32 v39, v21, v39
	v_mov_b32_e32 v20, v32
	v_mov_b32_e32 v21, v28
	v_mov_b32_e32 v28, v33
	v_pk_add_f32 v[20:21], v[20:21], v[28:29]
	v_mov_b32_e32 v28, v30
	v_mov_b32_e32 v29, v26
	v_pk_add_f32 v[20:21], v[28:29], v[20:21]
	v_mov_b32_e32 v26, v31
	v_pk_add_f32 v[20:21], v[26:27], v[20:21]
	s_waitcnt lgkmcnt(0)
	v_mov_b32_e32 v26, v20
	v_mov_b32_e32 v27, v21
	s_nop 1
	v_permlane32_swap_b32_e32 v26, v20
	v_permlane32_swap_b32_e32 v27, v21
	s_nop 1
	v_pk_add_f32 v[20:21], v[20:21], v[26:27]
	s_waitcnt lgkmcnt(0)
	v_mov_b32_e32 v26, v20
	v_mov_b32_e32 v27, v21
	s_nop 1
	v_permlane16_swap_b32_e32 v26, v20
	v_permlane16_swap_b32_e32 v27, v21
	s_nop 1
	v_pk_add_f32 v[20:21], v[20:21], v[26:27]
	s_waitcnt lgkmcnt(0)
	s_nop 1
	v_add_f32_dpp v21, v21, v21 row_mirror row_mask:0xf bank_mask:0xf
	v_add_f32_dpp v20, v20, v20 row_mirror row_mask:0xf bank_mask:0xf
	s_waitcnt lgkmcnt(0)
	s_nop 1
	v_add_f32_dpp v21, v21, v21 row_half_mirror row_mask:0xf bank_mask:0xf
	v_add_f32_dpp v20, v20, v20 row_half_mirror row_mask:0xf bank_mask:0xf
	s_waitcnt lgkmcnt(0)
	s_nop 1
	v_add_f32_dpp v21, v21, v21 quad_perm:[2,3,0,1] row_mask:0xf bank_mask:0xf
	v_add_f32_dpp v20, v20, v20 quad_perm:[2,3,0,1] row_mask:0xf bank_mask:0xf
	s_waitcnt lgkmcnt(0)
	s_nop 1
	v_add_f32_dpp v21, v21, v21 quad_perm:[1,0,3,2] row_mask:0xf bank_mask:0xf
	v_add_f32_dpp v20, v20, v20 quad_perm:[1,0,3,2] row_mask:0xf bank_mask:0xf
	s_nop 0
	v_pk_fma_f32 v[20:21], v[20:21], s[34:35], v[34:35] op_sel_hi:[1,0,0]
	s_nop 0
	v_mul_f32_e32 v26, 0x4b800000, v21
	v_cmp_gt_f32_e64 s[0:1], s72, v21
	v_cmp_gt_f32_e32 vcc, s72, v20
	s_nop 0
	v_cndmask_b32_e64 v21, v21, v26, s[0:1]
	v_rsq_f32_e32 v21, v21
	s_nop 0
	v_mul_f32_e32 v26, 0x45800000, v21
	v_cndmask_b32_e64 v21, v21, v26, s[0:1]
	v_mul_f32_e32 v22, v22, v21
	v_mul_f32_e32 v4, v22, v4
	v_mul_f32_e32 v22, v23, v21
	v_mul_f32_e32 v5, v22, v5
	v_mul_f32_e32 v4, v36, v4
	v_mul_f32_e32 v5, v38, v5
	v_cvt_pk_bf16_f32 v4, v4, v5
	v_mul_f32_e32 v5, v24, v21
	v_mul_f32_e32 v5, v5, v6
	v_mul_f32_e32 v6, v25, v21
	v_mul_f32_e32 v5, v37, v5
	v_mul_f32_e32 v6, v6, v7
	v_mul_f32_e32 v6, v39, v6
	v_cvt_pk_bf16_f32 v5, v5, v6
	global_store_dwordx2 v[12:13], v[4:5], off offset:3072
	v_mul_f32_e32 v4, 0x4b800000, v20
	v_cndmask_b32_e32 v4, v20, v4, vcc
	v_rsq_f32_e32 v4, v4
	s_waitcnt vmcnt(7)
	v_lshlrev_b32_e32 v21, 16, v18
	v_and_b32_e32 v22, 0xffff0000, v18
	v_lshlrev_b32_e32 v23, 16, v19
	v_mul_f32_e32 v5, 0x45800000, v4
	v_cndmask_b32_e32 v20, v4, v5, vcc
	ds_read_b128 v[4:7], v83 offset:7168
	v_mul_f32_e32 v16, v16, v20
	v_and_b32_e32 v18, 0xffff0000, v19
	s_waitcnt lgkmcnt(0)
	v_mul_f32_e32 v4, v16, v4
	v_mul_f32_e32 v16, 0xbfb8aa3b, v21
	v_exp_f32_e32 v16, v16
	s_nop 0
	v_add_f32_e32 v16, 1.0, v16
	s_nop 0
	v_rcp_f32_e32 v19, v16
	s_nop 0
	v_mul_f32_e32 v16, v21, v19
	v_mul_f32_e32 v4, v16, v4
	v_mul_f32_e32 v16, v17, v20
	v_mul_f32_e32 v5, v16, v5
	v_mul_f32_e32 v16, 0xbfb8aa3b, v22
	v_exp_f32_e32 v16, v16
	s_nop 0
	v_add_f32_e32 v16, 1.0, v16
	s_nop 0
	v_rcp_f32_e32 v17, v16
	s_nop 0
	v_mul_f32_e32 v16, v22, v17
	v_mul_f32_e32 v5, v16, v5
	v_cvt_pk_bf16_f32 v4, v4, v5
	v_mul_f32_e32 v5, v14, v20
	v_mul_f32_e32 v5, v5, v6
	v_mul_f32_e32 v6, 0xbfb8aa3b, v23
	v_exp_f32_e32 v6, v6
	s_nop 0
	v_add_f32_e32 v6, 1.0, v6
	s_nop 0
	v_rcp_f32_e32 v14, v6
	s_nop 0
	v_mul_f32_e32 v6, v23, v14
	v_mul_f32_e32 v5, v6, v5
	v_mul_f32_e32 v6, v15, v20
	v_mul_f32_e32 v6, v6, v7
	v_mul_f32_e32 v7, 0xbfb8aa3b, v18
	v_exp_f32_e32 v7, v7
	s_nop 0
	v_add_f32_e32 v7, 1.0, v7
	s_movk_i32 s0, 0x1fff
	v_cmp_lt_i32_e32 vcc, s0, v82
	v_rcp_f32_e32 v14, v7
	s_nop 0
	v_mul_f32_e32 v7, v18, v14
	s_or_b64 s[6:7], vcc, s[6:7]
	v_mul_f32_e32 v6, v7, v6
	v_cvt_pk_bf16_f32 v5, v5, v6
	global_store_dwordx2 v[12:13], v[4:5], off offset:3584
	s_andn2_b64 exec, exec, s[6:7]
	s_cbranch_execnz .LBB0_503
